# v017: group/dataflow syncs + SwiGLU epilogue + final-norm local rows (row-offset add moved away from its store)
# speedup vs baseline: 1.0052x; 1.0052x over previous
; __device__ __forceinline__ u32x4 pack8(const f32x4 v0, const f32x4 v1) { u32x4 w; w.x = cvt_pk_bf16(v0[0], v0[1]); w.y = cvt_pk_bf16(v0[2], v0[3]); w.z = cvt_pk_bf16(v1[0], v1[1]); w.w = cvt_pk_bf16(v1[2], v1[3]); return w; }
; __device__ __forceinline__ float sigm(float v) { return __builtin_amdgcn_rcpf(1.0f + __expf(-v)); }
;     __device__ __forceinline__ void operator()(const f32x4 (&acc)[2][2][4][2], const Unit& u, int wr, int wc, int fr_in, int fq_in) const {
;     ...
; #pragma unroll
;         for (int ai = 0; ai < 2; ++ai)
; #pragma unroll
;             for (int m = 0; m < 4; ++m) {
;                 f32x4 o[2];
; #pragma unroll
;                 for (int n = 0; n < 2; ++n) {
;                     const f32x4 g = acc[ai][0][m][n] * rstd[ai][m], up = acc[ai][1][m][n] * rstd[ai][m];
; #pragma unroll
;                     for (int e = 0; e < 4; ++e) o[n][e] = g[e] * sigm(g[e]) * up[e];
;                 }
;                 *(u32x4*)(act + (size_t)(row0 + ai * HALF + m * 16) * ldc + u.pn * HALF + wc * 32 + 8 * fq) = pack8(o[0], o[1]);
.LBB0_589:
	s_movk_i32 s4, 0x1600
	s_lshl_b32 s40, s24, 8
	v_mul_u32_u24_e32 v131, 0x1600, v182
	s_add_u32 s40, s6, s40
	s_addc_u32 s41, s7, 0
	v_mov_b32_e32 v178, 1.0
	v_mov_b32_e32 v179, 1.0
	s_add_u32 s40, s40, s90
	s_addc_u32 s41, s41, s91
	v_lshl_add_u32 v131, v187, 4, v131
	v_mul_f32_e32 v156, 0xbfb8aa3b, v184
	v_mul_f32_e32 v172, v184, v184
	v_pk_mul_f32 v[158:159], v[126:127], v[156:157] op_sel_hi:[1,0]
	v_pk_mul_f32 v[160:161], v[128:129], v[156:157] op_sel_hi:[1,0]
	v_pk_mul_f32 v[162:163], v[118:119], v[156:157] op_sel_hi:[1,0]
	v_pk_mul_f32 v[166:167], v[120:121], v[156:157] op_sel_hi:[1,0]
	v_exp_f32_e32 v158, v158
	v_exp_f32_e32 v159, v159
	v_pk_mul_f32 v[122:123], v[126:127], v[122:123]
	v_exp_f32_e32 v160, v160
	v_exp_f32_e32 v161, v161
	v_pk_mul_f32 v[124:125], v[128:129], v[124:125]
	v_exp_f32_e32 v162, v162
	v_exp_f32_e32 v163, v163
	v_pk_mul_f32 v[114:115], v[118:119], v[114:115]
	v_exp_f32_e32 v166, v166
	v_exp_f32_e32 v167, v167
	v_pk_mul_f32 v[116:117], v[120:121], v[116:117]
	v_pk_add_f32 v[158:159], v[158:159], v[178:179]
	v_pk_add_f32 v[160:161], v[160:161], v[178:179]
	v_pk_add_f32 v[162:163], v[162:163], v[178:179]
	v_pk_add_f32 v[166:167], v[166:167], v[178:179]
	v_rcp_f32_e32 v158, v158
	v_rcp_f32_e32 v159, v159
	v_pk_mul_f32 v[122:123], v[122:123], v[172:173] op_sel_hi:[1,0]
	v_rcp_f32_e32 v160, v160
	v_rcp_f32_e32 v161, v161
	v_pk_mul_f32 v[124:125], v[124:125], v[172:173] op_sel_hi:[1,0]
	v_rcp_f32_e32 v162, v162
	v_rcp_f32_e32 v163, v163
	v_pk_mul_f32 v[114:115], v[114:115], v[172:173] op_sel_hi:[1,0]
	v_rcp_f32_e32 v166, v166
	v_rcp_f32_e32 v167, v167
	v_pk_mul_f32 v[116:117], v[116:117], v[172:173] op_sel_hi:[1,0]
	v_mul_f32_e32 v156, 0xbfb8aa3b, v180
	v_mul_f32_e32 v172, v180, v180
	v_pk_mul_f32 v[122:123], v[122:123], v[158:159]
	v_pk_mul_f32 v[124:125], v[124:125], v[160:161]
	v_pk_mul_f32 v[114:115], v[114:115], v[162:163]
	v_pk_mul_f32 v[116:117], v[116:117], v[166:167]
	v_cvt_pk_bf16_f32 v132, v122, v123
	v_cvt_pk_bf16_f32 v133, v124, v125
	v_cvt_pk_bf16_f32 v134, v114, v115
	v_cvt_pk_bf16_f32 v135, v116, v117
	s_nop 0
	global_store_dwordx4 v131, v[132:135], s[40:41]
	v_pk_mul_f32 v[158:159], v[110:111], v[156:157] op_sel_hi:[1,0]
	v_pk_mul_f32 v[160:161], v[112:113], v[156:157] op_sel_hi:[1,0]
	v_pk_mul_f32 v[162:163], v[102:103], v[156:157] op_sel_hi:[1,0]
	v_pk_mul_f32 v[166:167], v[104:105], v[156:157] op_sel_hi:[1,0]
	v_add_u32_e32 v131, 0x16000, v131
	v_exp_f32_e32 v158, v158
	v_exp_f32_e32 v159, v159
	v_pk_mul_f32 v[106:107], v[110:111], v[106:107]
	v_exp_f32_e32 v160, v160
	v_exp_f32_e32 v161, v161
	v_pk_mul_f32 v[108:109], v[112:113], v[108:109]
	v_exp_f32_e32 v162, v162
	v_exp_f32_e32 v163, v163
	v_pk_mul_f32 v[98:99], v[102:103], v[98:99]
	v_exp_f32_e32 v166, v166
	v_exp_f32_e32 v167, v167
	v_pk_mul_f32 v[100:101], v[104:105], v[100:101]
	v_pk_add_f32 v[158:159], v[158:159], v[178:179]
	v_pk_add_f32 v[160:161], v[160:161], v[178:179]
	v_pk_add_f32 v[162:163], v[162:163], v[178:179]
	v_pk_add_f32 v[166:167], v[166:167], v[178:179]
	v_rcp_f32_e32 v158, v158
	v_rcp_f32_e32 v159, v159
	v_pk_mul_f32 v[106:107], v[106:107], v[172:173] op_sel_hi:[1,0]
	v_rcp_f32_e32 v160, v160
	v_rcp_f32_e32 v161, v161
	v_pk_mul_f32 v[108:109], v[108:109], v[172:173] op_sel_hi:[1,0]
	v_rcp_f32_e32 v162, v162
	v_rcp_f32_e32 v163, v163
	v_pk_mul_f32 v[98:99], v[98:99], v[172:173] op_sel_hi:[1,0]
	v_rcp_f32_e32 v166, v166
	v_rcp_f32_e32 v167, v167
	v_pk_mul_f32 v[100:101], v[100:101], v[172:173] op_sel_hi:[1,0]
	v_mul_f32_e32 v156, 0xbfb8aa3b, v176
	v_mul_f32_e32 v172, v176, v176
	v_pk_mul_f32 v[106:107], v[106:107], v[158:159]
	v_pk_mul_f32 v[108:109], v[108:109], v[160:161]
	v_pk_mul_f32 v[98:99], v[98:99], v[162:163]
	v_pk_mul_f32 v[100:101], v[100:101], v[166:167]
	v_cvt_pk_bf16_f32 v132, v106, v107
	v_cvt_pk_bf16_f32 v133, v108, v109
	v_cvt_pk_bf16_f32 v134, v98, v99
	v_cvt_pk_bf16_f32 v135, v100, v101
	s_nop 0
	global_store_dwordx4 v131, v[132:135], s[40:41]
	v_pk_mul_f32 v[158:159], v[94:95], v[156:157] op_sel_hi:[1,0]
	v_pk_mul_f32 v[160:161], v[96:97], v[156:157] op_sel_hi:[1,0]
	v_pk_mul_f32 v[162:163], v[86:87], v[156:157] op_sel_hi:[1,0]
	v_pk_mul_f32 v[166:167], v[88:89], v[156:157] op_sel_hi:[1,0]
	v_add_u32_e32 v131, 0x16000, v131
	v_exp_f32_e32 v158, v158
	v_exp_f32_e32 v159, v159
	v_pk_mul_f32 v[90:91], v[94:95], v[90:91]
	v_exp_f32_e32 v160, v160
	v_exp_f32_e32 v161, v161
	v_pk_mul_f32 v[92:93], v[96:97], v[92:93]
	v_exp_f32_e32 v162, v162
	v_exp_f32_e32 v163, v163
	v_pk_mul_f32 v[82:83], v[86:87], v[82:83]
	v_exp_f32_e32 v166, v166
	v_exp_f32_e32 v167, v167
	v_pk_mul_f32 v[84:85], v[88:89], v[84:85]
	v_pk_add_f32 v[158:159], v[158:159], v[178:179]
	v_pk_add_f32 v[160:161], v[160:161], v[178:179]
	v_pk_add_f32 v[162:163], v[162:163], v[178:179]
	v_pk_add_f32 v[166:167], v[166:167], v[178:179]
	v_rcp_f32_e32 v158, v158
	v_rcp_f32_e32 v159, v159
	v_pk_mul_f32 v[90:91], v[90:91], v[172:173] op_sel_hi:[1,0]
	v_rcp_f32_e32 v160, v160
	v_rcp_f32_e32 v161, v161
	v_pk_mul_f32 v[92:93], v[92:93], v[172:173] op_sel_hi:[1,0]
	v_rcp_f32_e32 v162, v162
	v_rcp_f32_e32 v163, v163
	v_pk_mul_f32 v[82:83], v[82:83], v[172:173] op_sel_hi:[1,0]
	v_rcp_f32_e32 v166, v166
	v_rcp_f32_e32 v167, v167
	v_pk_mul_f32 v[84:85], v[84:85], v[172:173] op_sel_hi:[1,0]
	v_mul_f32_e32 v156, 0xbfb8aa3b, v174
	v_mul_f32_e32 v172, v174, v174
	v_pk_mul_f32 v[90:91], v[90:91], v[158:159]
	v_pk_mul_f32 v[92:93], v[92:93], v[160:161]
	v_pk_mul_f32 v[82:83], v[82:83], v[162:163]
	v_pk_mul_f32 v[84:85], v[84:85], v[166:167]
	v_cvt_pk_bf16_f32 v132, v90, v91
	v_cvt_pk_bf16_f32 v133, v92, v93
	v_cvt_pk_bf16_f32 v134, v82, v83
; __device__ __forceinline__ u32x4 pack8(const f32x4 v0, const f32x4 v1) { u32x4 w; w.x = cvt_pk_bf16(v0[0], v0[1]); w.y = cvt_pk_bf16(v0[2], v0[3]); w.z = cvt_pk_bf16(v1[0], v1[1]); w.w = cvt_pk_bf16(v1[2], v1[3]); return w; }
; __device__ __forceinline__ float sigm(float v) { return __builtin_amdgcn_rcpf(1.0f + __expf(-v)); }
;     __device__ __forceinline__ void operator()(const f32x4 (&acc)[2][2][4][2], const Unit& u, int wr, int wc, int fr_in, int fq_in) const {
;     ...
; #pragma unroll
;         for (int ai = 0; ai < 2; ++ai)
; #pragma unroll
;             for (int m = 0; m < 4; ++m) {
;                 f32x4 o[2];
; #pragma unroll
;                 for (int n = 0; n < 2; ++n) {
;                     const f32x4 g = acc[ai][0][m][n] * rstd[ai][m], up = acc[ai][1][m][n] * rstd[ai][m];
; #pragma unroll
;                     for (int e = 0; e < 4; ++e) o[n][e] = g[e] * sigm(g[e]) * up[e];
;                 }
;                 *(u32x4*)(act + (size_t)(row0 + ai * HALF + m * 16) * ldc + u.pn * HALF + wc * 32 + 8 * fq) = pack8(o[0], o[1]);
	v_cvt_pk_bf16_f32 v135, v84, v85
	s_nop 0
	global_store_dwordx4 v131, v[132:135], s[40:41]
	v_pk_mul_f32 v[158:159], v[78:79], v[156:157] op_sel_hi:[1,0]
	v_pk_mul_f32 v[160:161], v[80:81], v[156:157] op_sel_hi:[1,0]
	v_pk_mul_f32 v[162:163], v[70:71], v[156:157] op_sel_hi:[1,0]
	v_pk_mul_f32 v[166:167], v[72:73], v[156:157] op_sel_hi:[1,0]
	v_add_u32_e32 v131, 0x16000, v131
	v_exp_f32_e32 v158, v158
	v_exp_f32_e32 v159, v159
	v_pk_mul_f32 v[74:75], v[78:79], v[74:75]
	v_exp_f32_e32 v160, v160
	v_exp_f32_e32 v161, v161
	v_pk_mul_f32 v[76:77], v[80:81], v[76:77]
	v_exp_f32_e32 v162, v162
	v_exp_f32_e32 v163, v163
	v_pk_mul_f32 v[66:67], v[70:71], v[66:67]
	v_exp_f32_e32 v166, v166
	v_exp_f32_e32 v167, v167
	v_pk_mul_f32 v[68:69], v[72:73], v[68:69]
	v_pk_add_f32 v[158:159], v[158:159], v[178:179]
	v_pk_add_f32 v[160:161], v[160:161], v[178:179]
	v_pk_add_f32 v[162:163], v[162:163], v[178:179]
	v_pk_add_f32 v[166:167], v[166:167], v[178:179]
	v_rcp_f32_e32 v158, v158
	v_rcp_f32_e32 v159, v159
	v_pk_mul_f32 v[74:75], v[74:75], v[172:173] op_sel_hi:[1,0]
	v_rcp_f32_e32 v160, v160
	v_rcp_f32_e32 v161, v161
	v_pk_mul_f32 v[76:77], v[76:77], v[172:173] op_sel_hi:[1,0]
	v_rcp_f32_e32 v162, v162
	v_rcp_f32_e32 v163, v163
	v_pk_mul_f32 v[66:67], v[66:67], v[172:173] op_sel_hi:[1,0]
	v_rcp_f32_e32 v166, v166
	v_rcp_f32_e32 v167, v167
	v_pk_mul_f32 v[68:69], v[68:69], v[172:173] op_sel_hi:[1,0]
	v_mul_f32_e32 v156, 0xbfb8aa3b, v170
	v_mul_f32_e32 v172, v170, v170
	v_pk_mul_f32 v[74:75], v[74:75], v[158:159]
	v_pk_mul_f32 v[76:77], v[76:77], v[160:161]
	v_pk_mul_f32 v[66:67], v[66:67], v[162:163]
	v_pk_mul_f32 v[68:69], v[68:69], v[166:167]
	v_cvt_pk_bf16_f32 v132, v74, v75
	v_cvt_pk_bf16_f32 v133, v76, v77
	v_cvt_pk_bf16_f32 v134, v66, v67
	v_cvt_pk_bf16_f32 v135, v68, v69
	s_nop 0
	global_store_dwordx4 v131, v[132:135], s[40:41]
	v_pk_mul_f32 v[158:159], v[62:63], v[156:157] op_sel_hi:[1,0]
	v_pk_mul_f32 v[160:161], v[64:65], v[156:157] op_sel_hi:[1,0]
	v_pk_mul_f32 v[162:163], v[54:55], v[156:157] op_sel_hi:[1,0]
	v_pk_mul_f32 v[166:167], v[56:57], v[156:157] op_sel_hi:[1,0]
	v_add_u32_e32 v131, 0x6e000, v131
	v_exp_f32_e32 v158, v158
	v_exp_f32_e32 v159, v159
	v_pk_mul_f32 v[58:59], v[62:63], v[58:59]
	v_exp_f32_e32 v160, v160
	v_exp_f32_e32 v161, v161
	v_pk_mul_f32 v[60:61], v[64:65], v[60:61]
	v_exp_f32_e32 v162, v162
	v_exp_f32_e32 v163, v163
	v_pk_mul_f32 v[50:51], v[54:55], v[50:51]
	v_exp_f32_e32 v166, v166
	v_exp_f32_e32 v167, v167
	v_pk_mul_f32 v[52:53], v[56:57], v[52:53]
	v_pk_add_f32 v[158:159], v[158:159], v[178:179]
	v_pk_add_f32 v[160:161], v[160:161], v[178:179]
	v_pk_add_f32 v[162:163], v[162:163], v[178:179]
	v_pk_add_f32 v[166:167], v[166:167], v[178:179]
	v_rcp_f32_e32 v158, v158
	v_rcp_f32_e32 v159, v159
	v_pk_mul_f32 v[58:59], v[58:59], v[172:173] op_sel_hi:[1,0]
	v_rcp_f32_e32 v160, v160
	v_rcp_f32_e32 v161, v161
	v_pk_mul_f32 v[60:61], v[60:61], v[172:173] op_sel_hi:[1,0]
	v_rcp_f32_e32 v162, v162
	v_rcp_f32_e32 v163, v163
	v_pk_mul_f32 v[50:51], v[50:51], v[172:173] op_sel_hi:[1,0]
	v_rcp_f32_e32 v166, v166
	v_rcp_f32_e32 v167, v167
	v_pk_mul_f32 v[52:53], v[52:53], v[172:173] op_sel_hi:[1,0]
	v_mul_f32_e32 v156, 0xbfb8aa3b, v168
	v_mul_f32_e32 v172, v168, v168
	v_pk_mul_f32 v[58:59], v[58:59], v[158:159]
	v_pk_mul_f32 v[60:61], v[60:61], v[160:161]
	v_pk_mul_f32 v[50:51], v[50:51], v[162:163]
	v_pk_mul_f32 v[52:53], v[52:53], v[166:167]
	v_cvt_pk_bf16_f32 v132, v58, v59
	v_cvt_pk_bf16_f32 v133, v60, v61
	v_cvt_pk_bf16_f32 v134, v50, v51
	v_cvt_pk_bf16_f32 v135, v52, v53
	s_nop 0
	global_store_dwordx4 v131, v[132:135], s[40:41]
	v_pk_mul_f32 v[158:159], v[46:47], v[156:157] op_sel_hi:[1,0]
	v_pk_mul_f32 v[160:161], v[48:49], v[156:157] op_sel_hi:[1,0]
	v_pk_mul_f32 v[162:163], v[38:39], v[156:157] op_sel_hi:[1,0]
	v_pk_mul_f32 v[166:167], v[40:41], v[156:157] op_sel_hi:[1,0]
	v_add_u32_e32 v131, 0x16000, v131
	v_exp_f32_e32 v158, v158
	v_exp_f32_e32 v159, v159
	v_pk_mul_f32 v[42:43], v[46:47], v[42:43]
	v_exp_f32_e32 v160, v160
	v_exp_f32_e32 v161, v161
	v_pk_mul_f32 v[44:45], v[48:49], v[44:45]
	v_exp_f32_e32 v162, v162
	v_exp_f32_e32 v163, v163
	v_pk_mul_f32 v[34:35], v[38:39], v[34:35]
	v_exp_f32_e32 v166, v166
	v_exp_f32_e32 v167, v167
	v_pk_mul_f32 v[36:37], v[40:41], v[36:37]
	v_pk_add_f32 v[158:159], v[158:159], v[178:179]
	v_pk_add_f32 v[160:161], v[160:161], v[178:179]
	v_pk_add_f32 v[162:163], v[162:163], v[178:179]
	v_pk_add_f32 v[166:167], v[166:167], v[178:179]
; __device__ __forceinline__ u32x4 pack8(const f32x4 v0, const f32x4 v1) { u32x4 w; w.x = cvt_pk_bf16(v0[0], v0[1]); w.y = cvt_pk_bf16(v0[2], v0[3]); w.z = cvt_pk_bf16(v1[0], v1[1]); w.w = cvt_pk_bf16(v1[2], v1[3]); return w; }
; __device__ __forceinline__ float sigm(float v) { return __builtin_amdgcn_rcpf(1.0f + __expf(-v)); }
;     __device__ __forceinline__ void operator()(const f32x4 (&acc)[2][2][4][2], const Unit& u, int wr, int wc, int fr_in, int fq_in) const {
;     ...
; #pragma unroll
;         for (int ai = 0; ai < 2; ++ai)
; #pragma unroll
;             for (int m = 0; m < 4; ++m) {
;                 f32x4 o[2];
; #pragma unroll
;                 for (int n = 0; n < 2; ++n) {
;                     const f32x4 g = acc[ai][0][m][n] * rstd[ai][m], up = acc[ai][1][m][n] * rstd[ai][m];
; #pragma unroll
;                     for (int e = 0; e < 4; ++e) o[n][e] = g[e] * sigm(g[e]) * up[e];
;                 }
;                 *(u32x4*)(act + (size_t)(row0 + ai * HALF + m * 16) * ldc + u.pn * HALF + wc * 32 + 8 * fq) = pack8(o[0], o[1]);
	v_rcp_f32_e32 v158, v158
	v_rcp_f32_e32 v159, v159
	v_pk_mul_f32 v[42:43], v[42:43], v[172:173] op_sel_hi:[1,0]
	v_rcp_f32_e32 v160, v160
	v_rcp_f32_e32 v161, v161
	v_pk_mul_f32 v[44:45], v[44:45], v[172:173] op_sel_hi:[1,0]
	v_rcp_f32_e32 v162, v162
	v_rcp_f32_e32 v163, v163
	v_pk_mul_f32 v[34:35], v[34:35], v[172:173] op_sel_hi:[1,0]
	v_rcp_f32_e32 v166, v166
	v_rcp_f32_e32 v167, v167
	v_pk_mul_f32 v[36:37], v[36:37], v[172:173] op_sel_hi:[1,0]
	v_mul_f32_e32 v156, 0xbfb8aa3b, v164
	v_mul_f32_e32 v172, v164, v164
	v_pk_mul_f32 v[42:43], v[42:43], v[158:159]
	v_pk_mul_f32 v[44:45], v[44:45], v[160:161]
	v_pk_mul_f32 v[34:35], v[34:35], v[162:163]
	v_pk_mul_f32 v[36:37], v[36:37], v[166:167]
	v_cvt_pk_bf16_f32 v132, v42, v43
	v_cvt_pk_bf16_f32 v133, v44, v45
	v_cvt_pk_bf16_f32 v134, v34, v35
	v_cvt_pk_bf16_f32 v135, v36, v37
	s_nop 0
	global_store_dwordx4 v131, v[132:135], s[40:41]
	v_pk_mul_f32 v[158:159], v[30:31], v[156:157] op_sel_hi:[1,0]
	v_pk_mul_f32 v[160:161], v[32:33], v[156:157] op_sel_hi:[1,0]
	v_pk_mul_f32 v[162:163], v[22:23], v[156:157] op_sel_hi:[1,0]
	v_pk_mul_f32 v[166:167], v[24:25], v[156:157] op_sel_hi:[1,0]
	v_add_u32_e32 v131, 0x16000, v131
	v_exp_f32_e32 v158, v158
	v_exp_f32_e32 v159, v159
	v_pk_mul_f32 v[26:27], v[30:31], v[26:27]
	v_exp_f32_e32 v160, v160
	v_exp_f32_e32 v161, v161
	v_pk_mul_f32 v[28:29], v[32:33], v[28:29]
	v_exp_f32_e32 v162, v162
	v_exp_f32_e32 v163, v163
	v_pk_mul_f32 v[18:19], v[22:23], v[18:19]
	v_exp_f32_e32 v166, v166
	v_exp_f32_e32 v167, v167
	v_pk_mul_f32 v[20:21], v[24:25], v[20:21]
	v_pk_add_f32 v[158:159], v[158:159], v[178:179]
	v_pk_add_f32 v[160:161], v[160:161], v[178:179]
	v_pk_add_f32 v[162:163], v[162:163], v[178:179]
	v_pk_add_f32 v[166:167], v[166:167], v[178:179]
	v_rcp_f32_e32 v158, v158
	v_rcp_f32_e32 v159, v159
	v_pk_mul_f32 v[26:27], v[26:27], v[172:173] op_sel_hi:[1,0]
	v_rcp_f32_e32 v160, v160
	v_rcp_f32_e32 v161, v161
	v_pk_mul_f32 v[28:29], v[28:29], v[172:173] op_sel_hi:[1,0]
	v_rcp_f32_e32 v162, v162
	v_rcp_f32_e32 v163, v163
	v_pk_mul_f32 v[18:19], v[18:19], v[172:173] op_sel_hi:[1,0]
	v_rcp_f32_e32 v166, v166
	v_rcp_f32_e32 v167, v167
	v_pk_mul_f32 v[20:21], v[20:21], v[172:173] op_sel_hi:[1,0]
	v_mul_f32_e32 v156, 0xbfb8aa3b, v130
	v_mul_f32_e32 v172, v130, v130
	v_pk_mul_f32 v[26:27], v[26:27], v[158:159]
	v_pk_mul_f32 v[28:29], v[28:29], v[160:161]
	v_pk_mul_f32 v[18:19], v[18:19], v[162:163]
	v_pk_mul_f32 v[20:21], v[20:21], v[166:167]
	v_cvt_pk_bf16_f32 v132, v26, v27
	v_cvt_pk_bf16_f32 v133, v28, v29
	v_cvt_pk_bf16_f32 v134, v18, v19
	v_cvt_pk_bf16_f32 v135, v20, v21
	s_nop 0
	global_store_dwordx4 v131, v[132:135], s[40:41]
	v_pk_mul_f32 v[158:159], v[14:15], v[156:157] op_sel_hi:[1,0]
	v_pk_mul_f32 v[160:161], v[16:17], v[156:157] op_sel_hi:[1,0]
	v_pk_mul_f32 v[162:163], v[6:7], v[156:157] op_sel_hi:[1,0]
	v_pk_mul_f32 v[166:167], v[8:9], v[156:157] op_sel_hi:[1,0]
	v_add_u32_e32 v131, 0x16000, v131
	v_exp_f32_e32 v158, v158
	v_exp_f32_e32 v159, v159
	v_pk_mul_f32 v[10:11], v[14:15], v[10:11]
	v_exp_f32_e32 v160, v160
	v_exp_f32_e32 v161, v161
	v_pk_mul_f32 v[12:13], v[16:17], v[12:13]
	v_exp_f32_e32 v162, v162
	v_exp_f32_e32 v163, v163
	v_pk_mul_f32 v[2:3], v[6:7], v[2:3]
	v_exp_f32_e32 v166, v166
	v_exp_f32_e32 v167, v167
	v_pk_mul_f32 v[4:5], v[8:9], v[4:5]
	v_pk_add_f32 v[158:159], v[158:159], v[178:179]
	v_pk_add_f32 v[160:161], v[160:161], v[178:179]
	v_pk_add_f32 v[162:163], v[162:163], v[178:179]
	v_pk_add_f32 v[166:167], v[166:167], v[178:179]
	v_rcp_f32_e32 v158, v158
	v_rcp_f32_e32 v159, v159
	v_pk_mul_f32 v[10:11], v[10:11], v[172:173] op_sel_hi:[1,0]
	v_rcp_f32_e32 v160, v160
	v_rcp_f32_e32 v161, v161
	v_pk_mul_f32 v[12:13], v[12:13], v[172:173] op_sel_hi:[1,0]
	v_rcp_f32_e32 v162, v162
	v_rcp_f32_e32 v163, v163
	v_pk_mul_f32 v[2:3], v[2:3], v[172:173] op_sel_hi:[1,0]
	v_rcp_f32_e32 v166, v166
	v_rcp_f32_e32 v167, v167
	v_pk_mul_f32 v[4:5], v[4:5], v[172:173] op_sel_hi:[1,0]
	s_nop 0
	v_pk_mul_f32 v[10:11], v[10:11], v[158:159]
	v_pk_mul_f32 v[12:13], v[12:13], v[160:161]
	v_pk_mul_f32 v[2:3], v[2:3], v[162:163]
	v_pk_mul_f32 v[4:5], v[4:5], v[166:167]
	v_cvt_pk_bf16_f32 v132, v10, v11
	v_cvt_pk_bf16_f32 v133, v12, v13
	v_cvt_pk_bf16_f32 v134, v2, v3
	v_cvt_pk_bf16_f32 v135, v4, v5
	s_nop 0
	global_store_dwordx4 v131, v[132:135], s[40:41]
	s_andn2_b64 vcc, exec, s[38:39]
	s_nop 4
	s_mov_b64 s[40:41], -1
	s_cbranch_vccnz .LBB0_578
	s_andn2_b64 vcc, exec, s[2:3]
	s_cbranch_vccnz .LBB0_577
	s_barrier
	s_branch .LBB0_577
